# XCD-local grid barriers (no L2 write-back, no cross-XCD rendezvous) at the 9 phase seams whose data stays inside one XCD, with a run-time placement check and fallback
# baseline (speedup 1.0000x reference)
_Z8mega_fwd4Args:
	s_mov_b32 s92, s2
	s_load_dwordx16 s[4:19], s[0:1], 0x0
	s_load_dwordx8 s[20:27], s[0:1], 0x40
	s_load_dword s30, s[0:1], 0x80
	s_load_dwordx4 s[36:39], s[0:1], 0x60
	s_load_dwordx2 s[2:3], s[0:1], 0x78
	v_and_b32_e32 v232, 0x3ff, v0
	v_cmp_gt_u32_e32 vcc, 2, v232
	s_waitcnt lgkmcnt(0)
	s_getreg_b32 s98, hwreg(HW_REG_XCC_ID, 0, 4)
	s_and_b32 s99, s92, 7
	s_cmp_lg_u32 s98, s99
	s_cselect_b32 s98, 1, 0
	s_cmp_lg_u32 s2, 0x100
	s_cselect_b32 s99, 1, 0
	s_or_b32 s98, s98, s99
	s_cmp_eq_u32 s98, 0
	s_cbranch_scc1 .Lpl_ok
	s_add_u32 s98, s38, 0xc35c0
	s_addc_u32 s99, s39, 0
	s_mov_b64 s[100:101], exec
	s_mov_b64 exec, 1
	v_mov_b32_e32 v100, 0
	v_mov_b32_e32 v101, 1
	s_nop 1
	global_atomic_add v100, v101, s[98:99]
	s_mov_b64 exec, s[100:101]
	s_waitcnt vmcnt(0)
.Lpl_ok:
	v_writelane_b32 v254, s2, 0
	s_nop 1
	v_writelane_b32 v254, s3, 1
	s_add_u32 s2, s0, 0x78
	s_addc_u32 s3, s1, 0
	s_and_saveexec_b64 s[28:29], vcc
	v_lshl_add_u32 v1, v232, 2, 0
	v_add_u32_e32 v1, 0x23fc0, v1
	v_mov_b32_e32 v2, 0
	ds_write_b32 v1, v2
	s_or_b64 exec, exec, s[28:29]
	s_load_dwordx2 s[0:1], s[0:1], 0x70
	v_cmp_eq_u32_e64 s[28:29], 0, v232
	s_waitcnt lgkmcnt(0)
	v_writelane_b32 v254, s0, 2
	s_nop 1
	v_writelane_b32 v254, s1, 3
	s_mov_b64 s[0:1], exec
	v_writelane_b32 v254, s28, 4
	s_nop 1
	v_writelane_b32 v254, s29, 5
	s_and_b64 s[28:29], s[0:1], s[28:29]
	s_mov_b64 exec, s[28:29]
	s_cbranch_execz .LBB0_4
	v_mov_b32_e32 v4, s16
	s_add_i32 s16, 0, 0x23f80
	v_mov_b32_e32 v2, s4
	v_mov_b32_e32 v3, s5
	v_mov_b32_e32 v5, s17
	v_mov_b32_e32 v1, s16
	s_add_i32 s16, 0, 0x23f90
	ds_write_b128 v1, v[2:5]
	v_mov_b32_e32 v2, s26
	v_mov_b32_e32 v3, s27
	v_mov_b32_e32 v4, s36
	v_mov_b32_e32 v5, s37
	v_mov_b32_e32 v1, s16
	ds_write_b128 v1, v[2:5]

.LBB0_141:
	s_or_b64 exec, exec, s[0:1]
	v_readlane_b32 s0, v254, 2
	v_readlane_b32 s1, v254, 3
	s_max_i32 s75, s0, 1
	s_cmp_ge_i32 s75, s1
	s_waitcnt lgkmcnt(0)
	s_barrier
	s_cbranch_scc1 .LBB0_738
	v_readlane_b32 s2, v254, 0
	s_lshl_b32 s34, s2, 5
	s_and_b32 s1, s2, 7
	s_cmp_eq_u32 s1, 0
	v_readlane_b32 s3, v254, 1
	s_cselect_b64 s[4:5], -1, 0
	s_mul_i32 s0, s3, s2
	v_writelane_b32 v254, s4, 11
	s_ashr_i32 s1, s2, 3
	s_ashr_i32 s62, s2, 31
	v_writelane_b32 v254, s5, 12
	s_mul_i32 s63, s0, s30
	s_add_u32 s0, s42, 0xc3520
	v_writelane_b32 v254, s1, 13
	s_addc_u32 s1, s43, 0
	v_writelane_b32 v254, s0, 14
	s_mov_b32 s79, 0
	v_mov_b32_e32 v0, 0
	v_writelane_b32 v254, s1, 15
	s_add_u32 s0, s42, 0xc3528
	s_addc_u32 s1, s43, 0
	v_writelane_b32 v254, s0, 16
	v_mov_b32_e32 v235, 0x358637bd
	s_mov_b32 s64, 0xf800000
	v_writelane_b32 v254, s1, 17
	s_add_u32 s0, s42, 0xc0200
	s_addc_u32 s1, s43, 0
	v_writelane_b32 v254, s0, 18
	s_cmp_eq_u32 s31, 15
	s_mov_b32 s66, 0xbfb8aa3b
	v_writelane_b32 v254, s1, 19
	s_cselect_b64 s[0:1], -1, 0
	v_writelane_b32 v254, s0, 20
	s_cmp_eq_u32 s31, 14
	s_mov_b32 s67, 0x1fffe0
	v_writelane_b32 v254, s1, 21
	s_cselect_b64 s[0:1], -1, 0
	v_writelane_b32 v254, s0, 22
	s_cmp_eq_u32 s31, 13
	s_movk_i32 s68, 0xb00
	v_writelane_b32 v254, s1, 23
	s_cselect_b64 s[0:1], -1, 0
	v_writelane_b32 v254, s0, 24
	s_cmp_eq_u32 s31, 12
	s_movk_i32 s69, 0x1600
	v_writelane_b32 v254, s1, 25
	s_cselect_b64 s[0:1], -1, 0
	v_writelane_b32 v254, s0, 26
	s_cmp_eq_u32 s31, 11
	s_movk_i32 s73, 0x161
	v_writelane_b32 v254, s1, 27
	s_cselect_b64 s[0:1], -1, 0
	v_writelane_b32 v254, s0, 28
	s_cmp_eq_u32 s31, 10
	v_mov_b32_e32 v234, 1
	v_writelane_b32 v254, s1, 29
	s_cselect_b64 s[0:1], -1, 0
	v_writelane_b32 v254, s0, 30
	s_cmp_eq_u32 s31, 9
	v_mbcnt_hi_u32_b32 v238, -1, v233
	v_writelane_b32 v254, s1, 31
	s_cselect_b64 s[0:1], -1, 0
	v_writelane_b32 v254, s0, 32
	s_cmp_eq_u32 s31, 8
	v_mov_b32_e32 v239, 0xf149f2ca
	v_writelane_b32 v254, s1, 33
	s_cselect_b64 s[0:1], -1, 0
	v_writelane_b32 v254, s0, 34
	s_cmp_eq_u32 s31, 7
	v_mov_b32_e32 v240, 0x3e38aa3b
	v_writelane_b32 v254, s1, 35
	s_cselect_b64 s[0:1], -1, 0
	v_writelane_b32 v254, s0, 36
	s_cmp_eq_u32 s31, 6
	v_mov_b64_e32 v[252:253], 0x200
	v_writelane_b32 v254, s1, 37
	s_cselect_b64 s[0:1], -1, 0
	v_writelane_b32 v254, s0, 38
	s_cmp_eq_u32 s31, 5
	v_mov_b64_e32 v[236:237], 0x1ff
	v_writelane_b32 v254, s1, 39
	s_cselect_b64 s[0:1], -1, 0
	v_writelane_b32 v254, s0, 40
	s_cmp_eq_u32 s31, 4
	v_mov_b32_e32 v241, 0xf78
	v_writelane_b32 v254, s1, 41
	s_cselect_b64 s[0:1], -1, 0
	v_writelane_b32 v254, s0, 42
	s_cmp_eq_u32 s31, 3
	s_mov_b64 s[90:91], 0x80
	v_writelane_b32 v254, s1, 43
	s_cselect_b64 s[0:1], -1, 0
	v_writelane_b32 v254, s0, 44
	s_cmp_eq_u32 s31, 2
	s_nop 0
	v_writelane_b32 v254, s1, 45
	s_cselect_b64 s[0:1], -1, 0
	v_writelane_b32 v254, s0, 46
	s_cmp_eq_u32 s31, 1
	s_nop 0
	v_writelane_b32 v254, s1, 47
	s_cselect_b64 s[0:1], -1, 0
	v_writelane_b32 v254, s0, 48
	s_cmp_eq_u32 s31, 0
	s_nop 0
	v_writelane_b32 v254, s1, 49
	s_cselect_b64 s[0:1], -1, 0
	v_writelane_b32 v254, s0, 50
	s_nop 1
	v_writelane_b32 v254, s1, 51
	s_lshl_b32 s0, s31, 8
	s_add_u32 s0, s28, s0
	s_addc_u32 s1, s29, 0
	s_add_u32 s4, s0, 0x1400
	s_addc_u32 s5, s1, 0
	v_writelane_b32 v254, s4, 52
	s_add_u32 s0, s0, 0x2400
	s_addc_u32 s1, s1, 0
	v_writelane_b32 v254, s5, 53
	v_writelane_b32 v254, s0, 54
	s_nop 1
	v_writelane_b32 v254, s1, 55
	s_add_u32 s0, s42, 0xc3400
	s_addc_u32 s1, s43, 0
	v_writelane_b32 v254, s0, 56
	s_nop 1
	v_writelane_b32 v254, s1, 57
	s_add_u32 s0, s42, 0xc3500
	s_addc_u32 s1, s43, 0
	v_writelane_b32 v254, s0, 58
	s_ashr_i32 s35, s34, 31
	s_add_i32 s65, 0, 0x4000
	v_writelane_b32 v254, s1, 59
	s_lshl_b64 s[0:1], s[34:35], 12
	v_writelane_b32 v254, s0, 60
	s_add_i32 s74, 0, 0x23f98
	s_nop 0
	v_writelane_b32 v254, s1, 61
	s_lshl_b64 s[0:1], s[34:35], 6
	v_writelane_b32 v254, s0, 62
	s_nop 1
	v_writelane_b32 v254, s1, 63
	s_lshl_b64 s[0:1], s[34:35], 11
	v_writelane_b32 v255, s0, 0
	s_nop 1
	v_writelane_b32 v255, s1, 1
	s_lshl_b32 s0, s2, 7
	v_writelane_b32 v255, s0, 2
	s_lshl_b32 s0, s2, 6
	v_writelane_b32 v255, s0, 3
	s_add_i32 s0, 0, 0x23f90
	v_writelane_b32 v255, s0, 4
	s_add_i32 s0, 0, 0x300
	v_writelane_b32 v255, s0, 5
	s_add_i32 s0, 0, 0x23f88
	v_writelane_b32 v255, s0, 6
	s_add_i32 s0, 0, 0x23f80
	v_writelane_b32 v255, s0, 7
	s_add_i32 s0, 0, 0x23fc0
	v_writelane_b32 v255, s0, 8
	s_add_i32 s0, 0, 0x23fc4
	v_writelane_b32 v255, s0, 9
	v_writelane_b32 v255, s92, 10
	v_writelane_b32 v255, s34, 11
	s_nop 1
	v_writelane_b32 v255, s35, 12
	v_writelane_b32 v255, s62, 13
	v_writelane_b32 v255, s63, 14
	v_writelane_b32 v255, s65, 15
	v_writelane_b32 v255, s74, 16
	s_add_u32 s98, s42, 0xc35c0
	s_addc_u32 s99, s43, 0
	v_mov_b32_e32 v100, 0
	s_nop 1
	global_load_dword v100, v100, s[98:99] sc1
	s_waitcnt vmcnt(0)
	v_readfirstlane_b32 s98, v100
	s_nop 3
	v_writelane_b32 v255, s98, 60
	s_branch .LBB0_147

.LBB0_719:
	s_andn2_saveexec_b64 s[2:3], s[2:3]
	s_cbranch_execz .LBB0_144
	v_readlane_b32 s4, v255, 60
	s_lshr_b32 s5, 0x39d6, s75
	s_and_b32 s5, s5, 1
	s_nop 1
	s_cmp_eq_u32 s4, 0
	s_cselect_b32 s5, s5, 0
	s_cmp_eq_u32 s5, 1
	s_cbranch_scc1 .Lbar_local
	s_mov_b64 s[2:3], exec
	buffer_wbl2 sc1
	s_waitcnt lgkmcnt(0)
	s_waitcnt vmcnt(0)
	v_mbcnt_lo_u32_b32 v1, s2, 0
	v_mbcnt_hi_u32_b32 v1, s3, v1
	v_cmp_eq_u32_e32 vcc, 0, v1
	s_and_saveexec_b64 s[4:5], vcc
	s_cbranch_execz .LBB0_722
	s_bcnt1_i32_b64 s2, s[2:3]
	v_mov_b32_e32 v3, s2
	v_readlane_b32 s2, v254, 56
	v_readlane_b32 s3, v254, 57
	s_nop 4
	global_atomic_add v3, v0, v3, s[2:3] sc0

.Lbar_local:
	s_mov_b64 s[2:3], exec
	v_mbcnt_lo_u32_b32 v1, s2, 0
	v_mbcnt_hi_u32_b32 v1, s3, v1
	v_cmp_eq_u32_e32 vcc, 0, v1
	s_waitcnt vmcnt(0)
	buffer_inv sc1
	s_and_saveexec_b64 s[4:5], vcc
	s_cbranch_execz .LBB0_143
	s_bcnt1_i32_b64 s2, s[2:3]
	v_mov_b32_e32 v1, s2
	v_readlane_b32 s2, v254, 54
	v_readlane_b32 s3, v254, 55
	s_nop 4
	global_atomic_add v0, v1, s[2:3]
	s_branch .LBB0_143
